# in-projection tile-to-workgroup remap (expensive vb/q/kv tile kinds onto the workgroups with one unit less) on top of the faster S5 tables item
# speedup vs baseline: 1.0046x; 1.0003x over previous
.LBB0_68:
	s_or_b64 exec, exec, s[4:5]
	s_add_u32 s14, s24, 0xda40000
	s_addc_u32 s15, s25, 0
	v_writelane_b32 v251, s14, 10
	s_add_u32 s4, s24, 0xfa40000
	s_addc_u32 s5, s25, 0
	v_writelane_b32 v251, s15, 11
	v_writelane_b32 v251, s4, 12
	v_mov_b32_e32 v1, 0
	v_add_u32_e32 v215, 0xfffffe00, v200
	v_writelane_b32 v251, s5, 13
	s_add_u32 s4, s24, 0x13a40000
	s_addc_u32 s5, s25, 0
	s_add_u32 s16, s24, 0x20e40000
	s_addc_u32 s17, s25, 0
	s_add_u32 s18, s24, 0x21e40000
	s_addc_u32 s19, s25, 0
	s_add_u32 s20, s24, 0x24e40000
	s_addc_u32 s21, s25, 0
	s_ashr_i32 s55, s54, 31
	v_writelane_b32 v251, s4, 14
	s_cmpk_lt_i32 s54, 0x6a0
	s_cselect_b64 s[22:23], -1, 0
	v_writelane_b32 v251, s5, 15
	s_add_u32 s4, s24, 0x26e40000
	v_writelane_b32 v251, s4, 16
	s_addc_u32 s4, s25, 0
	v_writelane_b32 v251, s4, 17
	s_add_u32 s4, s24, 0x27e40000
	s_addc_u32 s5, s25, 0
	v_writelane_b32 v251, s4, 18
	v_lshlrev_b32_e32 v218, 2, v200
	v_mov_b32_e32 v219, 0x358637bd
	v_writelane_b32 v251, s5, 19
	s_add_u32 s4, s24, 0x28040000
	v_writelane_b32 v251, s4, 20
	s_addc_u32 s4, s25, 0
	v_writelane_b32 v251, s4, 21
	s_add_u32 s4, s24, 0xda20000
	s_addc_u32 s5, s25, 0
	v_writelane_b32 v251, s4, 22
	v_mov_b32_e32 v220, 0x260
	v_mov_b32_e32 v221, 1
	v_writelane_b32 v251, s5, 23
	s_add_u32 s4, s24, 0x28064000
	v_writelane_b32 v251, s4, 24
	s_addc_u32 s4, s25, 0
	v_writelane_b32 v251, s4, 25
	s_add_u32 s4, s24, 0x28074000
	s_addc_u32 s5, s25, 0
	v_writelane_b32 v251, s4, 26
	v_mov_b64_e32 v[202:203], 0x6a0
	v_mov_b64_e32 v[204:205], 0x69f
	v_writelane_b32 v251, s5, 27
	s_not_b32 s4, s54
	s_add_i32 s10, s26, s4
	s_cmp_lt_i32 s10, 64
	s_cselect_b64 s[4:5], -1, 0
	v_writelane_b32 v251, s4, 28
	v_mbcnt_hi_u32_b32 v217, -1, v50
	v_mov_b32_e32 v222, 0xfffa0000
	v_writelane_b32 v251, s5, 29
	s_lshr_b32 s4, s55, 29
	s_add_i32 s4, s54, s4
	s_ashr_i32 s5, s4, 3
	s_and_b32 s4, s4, -8
	s_sub_i32 s6, s54, s4
	s_add_u32 s4, s24, 0x9600000
	v_writelane_b32 v251, s4, 30
	s_addc_u32 s4, s25, 0
	v_writelane_b32 v251, s4, 31
	s_add_u32 s4, s24, 0x9a10000
	v_writelane_b32 v251, s4, 32
	s_addc_u32 s4, s25, 0
	v_writelane_b32 v251, s4, 33
	s_add_u32 s4, s24, 0xba10000
	v_writelane_b32 v251, s4, 34
	s_addc_u32 s4, s25, 0
	v_writelane_b32 v251, s4, 35
	s_add_u32 s4, s24, 0xda10000
	v_writelane_b32 v251, s4, 36
	s_addc_u32 s4, s25, 0
	v_writelane_b32 v251, s4, 37
	s_add_i32 s4, 0, 0x20040
	s_ashr_i32 s7, s26, 31
	s_add_u32 s12, s24, 0x28060200
	s_addc_u32 s13, s25, 0
	v_writelane_b32 v251, s7, 38
	s_add_u32 s34, s24, 0x28060400
	v_writelane_b32 v251, s12, 39
	s_addc_u32 s35, s25, 0
	v_lshl_add_u32 v214, v200, 2, s4
	v_writelane_b32 v251, s13, 40
	s_add_u32 s12, s24, 0x28060500
	s_addc_u32 s13, s25, 0
	v_writelane_b32 v251, s12, 41
	v_mov_b32_e32 v223, 0xf149f2ca
	v_mov_b64_e32 v[206:207], 0x80
	v_writelane_b32 v251, s13, 42
	s_add_u32 s12, s24, 0x28060600
	s_addc_u32 s13, s25, 0
	v_writelane_b32 v251, s12, 43
	v_mov_b64_e32 v[208:209], 0x7f
	v_mov_b64_e32 v[210:211], 0x100
	v_writelane_b32 v251, s13, 44
	s_add_u32 s12, s24, 0x28060700
	s_addc_u32 s13, s25, 0
	v_writelane_b32 v251, s12, 45
	v_mov_b64_e32 v[212:213], 0xff
	s_movk_i32 s78, 0x6a00
	v_writelane_b32 v251, s13, 46
	s_add_u32 s12, s24, 0x28060800
	s_addc_u32 s13, s25, 0
	v_writelane_b32 v251, s12, 47
	s_nop 1
	v_writelane_b32 v251, s13, 48
	s_add_u32 s12, s24, 0x28060900
	s_addc_u32 s13, s25, 0
	v_writelane_b32 v251, s12, 49
	s_nop 1
	v_writelane_b32 v251, s13, 50
	s_add_u32 s12, s24, 0x28060a00
	s_addc_u32 s13, s25, 0
	v_writelane_b32 v251, s12, 51
	s_nop 1
	v_writelane_b32 v251, s13, 52
	s_add_u32 s12, s24, 0x28060b00
	s_addc_u32 s13, s25, 0
	v_writelane_b32 v251, s12, 53
	s_nop 1
	v_writelane_b32 v251, s13, 54
	s_add_u32 s12, s24, 0x28060c00
	s_addc_u32 s13, s25, 0
	v_writelane_b32 v251, s12, 55
	s_nop 1
	v_writelane_b32 v251, s13, 56
	s_add_u32 s12, s24, 0x28060d00
	s_addc_u32 s13, s25, 0
	v_writelane_b32 v251, s12, 57
	s_nop 1
	v_writelane_b32 v251, s13, 58
	s_add_u32 s12, s24, 0x28060e00
	s_addc_u32 s13, s25, 0
	v_writelane_b32 v251, s12, 59
	s_nop 1
	v_writelane_b32 v251, s13, 60
	s_add_u32 s12, s24, 0x28060f00
	s_addc_u32 s13, s25, 0
	v_writelane_b32 v251, s12, 61
	s_nop 1
	v_writelane_b32 v251, s13, 62
	s_add_u32 s12, s24, 0x28061000
	s_addc_u32 s13, s25, 0
	v_writelane_b32 v251, s12, 63
	s_nop 1
	v_writelane_b32 v252, s13, 0
	s_add_u32 s12, s24, 0x28061100
	s_addc_u32 s13, s25, 0
	v_writelane_b32 v252, s12, 1
	s_nop 1
	v_writelane_b32 v252, s13, 2
	s_add_u32 s12, s24, 0x28061200
	s_addc_u32 s13, s25, 0
	v_writelane_b32 v252, s12, 3
	s_nop 1
	v_writelane_b32 v252, s13, 4
	s_add_u32 s12, s24, 0x28061300
	s_addc_u32 s13, s25, 0
	v_writelane_b32 v252, s12, 5
	s_cmp_eq_u32 s8, 15
	s_nop 0
	v_writelane_b32 v252, s13, 6
	s_cselect_b64 s[12:13], -1, 0
	v_writelane_b32 v252, s12, 7
	s_cmp_eq_u32 s8, 14
	s_nop 0
	v_writelane_b32 v252, s13, 8
	s_cselect_b64 s[12:13], -1, 0
	v_writelane_b32 v252, s12, 9
	s_cmp_eq_u32 s8, 13
	s_nop 0
	v_writelane_b32 v252, s13, 10
	s_cselect_b64 s[12:13], -1, 0
	v_writelane_b32 v252, s12, 11
	s_cmp_eq_u32 s8, 12
	s_nop 0
	v_writelane_b32 v252, s13, 12
	s_cselect_b64 s[12:13], -1, 0
	v_writelane_b32 v252, s12, 13
	s_cmp_eq_u32 s8, 11
	s_nop 0
	v_writelane_b32 v252, s13, 14
	s_cselect_b64 s[12:13], -1, 0
	v_writelane_b32 v252, s12, 15
	s_cmp_eq_u32 s8, 10
	s_nop 0
	v_writelane_b32 v252, s13, 16
	s_cselect_b64 s[12:13], -1, 0
	v_writelane_b32 v252, s12, 17
	s_cmp_eq_u32 s8, 9
	s_nop 0
	v_writelane_b32 v252, s13, 18
	s_cselect_b64 s[12:13], -1, 0
	v_writelane_b32 v252, s12, 19
	s_cmp_eq_u32 s8, 8
	s_nop 0
	v_writelane_b32 v252, s13, 20
	s_cselect_b64 s[12:13], -1, 0
	v_writelane_b32 v252, s12, 21
	s_cmp_eq_u32 s8, 7
	s_nop 0
	v_writelane_b32 v252, s13, 22
	s_cselect_b64 s[12:13], -1, 0
	v_writelane_b32 v252, s12, 23
	s_cmp_eq_u32 s8, 6
	s_nop 0
	v_writelane_b32 v252, s13, 24
	s_cselect_b64 s[12:13], -1, 0
	v_writelane_b32 v252, s12, 25
	s_cmp_eq_u32 s8, 5
	s_nop 0
	v_writelane_b32 v252, s13, 26
	s_cselect_b64 s[12:13], -1, 0
	v_writelane_b32 v252, s12, 27
	s_cmp_eq_u32 s8, 4
	s_nop 0
	v_writelane_b32 v252, s13, 28
	s_cselect_b64 s[12:13], -1, 0
	v_writelane_b32 v252, s12, 29
	s_cmp_eq_u32 s8, 3
	s_nop 0
	v_writelane_b32 v252, s13, 30
	s_cselect_b64 s[12:13], -1, 0
	v_writelane_b32 v252, s12, 31
	s_cmp_eq_u32 s8, 2
	s_nop 0
	v_writelane_b32 v252, s13, 32
	s_cselect_b64 s[12:13], -1, 0
	v_writelane_b32 v252, s12, 33
	s_cmp_eq_u32 s8, 1
	s_nop 0
	v_writelane_b32 v252, s13, 34
	s_cselect_b64 s[12:13], -1, 0
	v_writelane_b32 v252, s12, 35
	s_cmp_eq_u32 s8, 0
	s_nop 0
	v_writelane_b32 v252, s13, 36
	s_cselect_b64 s[12:13], -1, 0
	s_lshl_b32 s7, s9, 2
	s_add_u32 s2, s2, s7
	s_addc_u32 s3, s3, 0
	v_writelane_b32 v252, s12, 37
	s_add_u32 s8, s2, 0x1400
	s_addc_u32 s9, s3, 0
	v_writelane_b32 v252, s13, 38
	v_writelane_b32 v252, s8, 39
	s_add_u32 s2, s2, 0x2400
	s_addc_u32 s3, s3, 0
	v_writelane_b32 v252, s9, 40
	v_writelane_b32 v252, s2, 41
	s_nop 1
	v_writelane_b32 v252, s3, 42
	s_add_u32 s2, s24, 0x28063400
	s_addc_u32 s3, s25, 0
	v_writelane_b32 v252, s2, 43
	s_nop 1
	v_writelane_b32 v252, s3, 44
	s_add_u32 s2, s24, 0x28063500
	s_addc_u32 s3, s25, 0
	v_writelane_b32 v252, s2, 45
	s_cmpk_lt_i32 s54, 0x300
	s_nop 0
	v_writelane_b32 v252, s3, 46
	s_cselect_b64 s[2:3], -1, 0
	v_writelane_b32 v252, s2, 47
	s_nop 1
	v_writelane_b32 v252, s3, 48
	s_add_u32 s2, s24, 0x26e40000
	s_addc_u32 s3, s25, 0
	v_writelane_b32 v252, s2, 49
	s_nop 1
	v_writelane_b32 v252, s3, 50
	s_add_u32 s2, s24, 0x28040000
	v_writelane_b32 v252, s2, 51
	s_addc_u32 s2, s25, 0
	v_writelane_b32 v252, s2, 52
	s_add_u32 s2, s24, 0x13a40000
	s_addc_u32 s3, s25, 0
	v_writelane_b32 v252, s2, 53
	s_nop 1
	v_writelane_b32 v252, s3, 54
	s_add_u32 s2, s24, 0x22e40000
	s_addc_u32 s3, s25, 0
	v_writelane_b32 v252, s2, 55
	s_nop 1
	v_writelane_b32 v252, s3, 56
	s_add_u32 s2, s24, 0x28074000
	s_addc_u32 s3, s25, 0
	v_writelane_b32 v252, s2, 57
	s_nop 1
	v_writelane_b32 v252, s3, 58
	s_add_u32 s2, s24, 0x20e40000
	v_writelane_b32 v252, s2, 59
	s_addc_u32 s2, s25, 0
	s_cmpk_gt_i32 s54, 0x7f
	v_writelane_b32 v252, s2, 60
	s_cselect_b32 s2, s10, 0x100
	s_add_i32 s3, s26, 0xffffff80
	s_cmpk_gt_i32 s26, 0x80
	s_cselect_b32 s13, s2, s54
	s_cselect_b32 s28, s3, s26
	s_cmpk_lt_i32 s13, 0x100
	v_writelane_b32 v252, s10, 61
	s_cselect_b64 s[2:3], -1, 0
	v_writelane_b32 v252, s2, 62
	s_nop 1
	v_writelane_b32 v252, s3, 63
	s_add_u32 s2, s24, 0x6a00000
	v_writelane_b32 v253, s2, 0
	s_addc_u32 s2, s25, 0
	s_cmp_gt_i32 s54, -1
	s_cselect_b32 s29, s54, 0x100000
	s_cmpk_lt_u32 s29, 0x80
	v_writelane_b32 v253, s2, 1
	s_cselect_b64 s[2:3], -1, 0
	v_writelane_b32 v253, s2, 2
	s_nop 1
	v_writelane_b32 v253, s3, 3
	s_lshl_b32 s2, s29, 2
	s_and_b32 s2, s2, 28
	s_add_u32 s3, s24, 0x6e00000
	v_writelane_b32 v253, s3, 4
	s_addc_u32 s3, s25, 0
	s_cmpk_lt_i32 s54, 0x100
	v_writelane_b32 v253, s3, 5
	s_cselect_b64 s[8:9], -1, 0
	v_writelane_b32 v253, s8, 6
	s_lshl_b32 s3, s6, 5
	s_add_u32 s7, s24, 0x8600000
	v_writelane_b32 v253, s9, 7
	s_load_dwordx4 s[8:11], s[0:1], 0x0
	v_writelane_b32 v253, s7, 8
	s_addc_u32 s7, s25, 0
	v_writelane_b32 v253, s7, 9
	s_movk_i32 s7, 0xd5
	s_waitcnt lgkmcnt(0)
	s_add_u32 s10, s10, 0x2000
	v_writelane_b32 v253, s8, 10
	s_nop 1
	v_writelane_b32 v253, s9, 11
	v_writelane_b32 v253, s10, 12
	v_writelane_b32 v253, s11, 13
	s_addc_u32 s11, s11, 0
	s_add_u32 s8, s24, 0x2806c000
	s_addc_u32 s9, s25, 0
	s_cmp_lt_i32 s6, 0
	s_cselect_b32 s7, s7, 0xd4
	v_writelane_b32 v253, s10, 14
	s_mul_i32 s7, s6, s7
	s_mul_i32 s6, s6, 33
	v_writelane_b32 v253, s11, 15
	s_cselect_b32 s3, s6, s3
	s_add_i32 s7, s7, s5
	v_writelane_b32 v253, s8, 16
	s_mul_hi_i32 s6, s7, 0x4d4873ed
	s_nop 0
	v_writelane_b32 v253, s9, 17
	s_lshr_b32 s8, s6, 31
	s_ashr_i32 s6, s6, 6
	s_add_i32 s6, s6, s8
	s_mul_i32 s8, s6, 0xd4
	s_sub_i32 s8, s7, s8
	s_bfe_u32 s7, s8, 0x2001d
	s_add_i32 s7, s8, s7
	s_sext_i32_i16 s9, s7
	s_ashr_i32 s9, s9, 2
	s_mul_i32 s10, s6, 7
	s_add_i32 s10, s10, s9
	s_mul_hi_i32 s9, s10, 0x4d4873ed
	s_lshr_b32 s11, s9, 31
	s_ashr_i32 s9, s9, 4
	s_add_i32 s9, s9, s11
	s_bfe_u32 s11, s29, 0x20003
	s_or_b32 s30, s2, s11
	s_lshl_b32 s11, s6, 2
	s_sub_i32 s2, 32, s11
	s_min_i32 s12, s2, 4
	s_and_b32 s2, s7, 0xfffc
	s_sub_i32 s2, s8, s2
	v_writelane_b32 v253, s29, 18
	s_sext_i32_i16 s2, s2
	s_mul_i32 s9, s9, 53
	s_bfe_u32 s6, s29, 0x60005
	v_writelane_b32 v253, s30, 19
	s_sub_i32 s36, s10, s9
	v_readlane_b32 s98, v251, 0
	s_nop 3
	s_and_b32 s99, s98, 7
	s_lshr_b32 s98, s98, 5
	s_cmp_lt_u32 s98, 5
	s_cbranch_scc1 .Lmp0_A
	s_sub_i32 vcc_lo, 9, s98
	s_mov_b32 vcc_lo, s99
	s_cmp_eq_u32 s98, 5
	s_cbranch_scc0 .Lmp0_H6
	s_and_b32 s36, vcc_lo, 1
	s_and_b32 vcc_lo, vcc_lo, 2
	s_lshl_b32 vcc_lo, vcc_lo, 2
	s_add_i32 s36, s36, vcc_lo
	s_add_i32 s36, s36, 12
	s_branch .Lmp0_D
.Lmp0_H6:
	s_cmp_eq_u32 s98, 6
	s_cbranch_scc0 .Lmp0_H7
	s_mul_i32 vcc_hi, vcc_lo, 11
	s_lshr_b32 vcc_hi, vcc_hi, 5
	s_mul_i32 vcc_hi, vcc_hi, 3
	s_sub_i32 vcc_lo, vcc_lo, vcc_hi
	s_min_u32 s36, vcc_lo, 1
	s_lshl_b32 s36, s36, 3
	s_lshr_b32 vcc_lo, vcc_lo, 1
	s_lshl_b32 vcc_lo, vcc_lo, 1
	s_add_i32 s36, s36, vcc_lo
	s_add_i32 s36, s36, 14
	s_branch .Lmp0_D
.Lmp0_H7:
	s_and_b32 s36, vcc_lo, 1
	s_lshl_b32 s36, s36, 3
	s_add_i32 s36, s36, 15
	s_branch .Lmp0_D
.Lmp0_A:
	s_mov_b32 s36, s98
.Lmp0_L:
	s_mul_i32 vcc_lo, s99, 5
	s_add_i32 s36, s36, vcc_lo
	s_cmp_ge_u32 s36, 44
	s_cbranch_scc0 .Lmp0_L2
	s_sub_i32 s36, s36, 44
.Lmp0_L2:
	s_cmp_lt_u32 s36, 12
	s_cbranch_scc1 .Lmp0_D
	s_cmp_lt_u32 s36, 16
	s_cselect_b32 vcc_lo, 4, 9
	s_add_i32 s36, s36, vcc_lo
.Lmp0_D:
	s_add_i32 s38, s11, s2
	s_lshl_b32 s2, s30, 19
	v_writelane_b32 v253, s6, 20
	s_lshl_b32 s6, s6, 19
	v_writelane_b32 v253, s6, 21
	s_add_u32 s6, s16, s2
	v_writelane_b32 v253, s16, 22
	s_addc_u32 s7, s17, 0
	s_mov_b32 s10, s36
	v_writelane_b32 v253, s17, 23
	s_add_u32 s16, s6, 0x40000
	v_writelane_b32 v253, s6, 24
	s_addc_u32 s17, s7, 0
	s_add_i32 s2, s3, s5
	s_ashr_i32 s3, s2, 31
	s_lshr_b32 s3, s3, 27
	s_add_i32 s3, s2, s3
	s_and_b32 s5, s3, 0xffe0
	s_sub_i32 s2, s2, s5
	s_bfe_i32 s5, s2, 0x80000
	s_bfe_u32 s5, s5, 0x2000d
	s_add_i32 s5, s2, s5
	v_writelane_b32 v253, s7, 25
	s_and_b32 s6, s5, 0xfc
	s_sub_i32 s2, s2, s6
	s_ashr_i32 s3, s3, 5
	s_bfe_i32 s5, s5, 0x80000
	v_writelane_b32 v253, s16, 26
	s_lshl_b32 s3, s3, 2
	s_sext_i32_i16 s5, s5
	s_sext_i32_i8 s2, s2
	v_writelane_b32 v253, s17, 27
	s_add_i32 s16, s3, s2
	s_ashr_i32 s2, s5, 2
	v_writelane_b32 v253, s2, 28
	s_mov_b32 s6, s38
	v_writelane_b32 v253, s6, 29
	s_ashr_i32 s39, s38, 31
	s_ashr_i32 s37, s36, 31
	v_writelane_b32 v253, s7, 30
	v_writelane_b32 v253, s10, 31
	s_lshr_b32 s2, s5, 2
	s_lshl_b64 s[6:7], s[38:39], 20
	v_writelane_b32 v253, s11, 32
	s_lshl_b64 s[30:31], s[36:37], 20
	v_writelane_b32 v253, s30, 33
	s_add_u32 s6, s14, s6
	s_addc_u32 s7, s15, s7
	v_writelane_b32 v253, s31, 34
	s_add_u32 s14, s6, 0x80000
	v_writelane_b32 v253, s6, 35
	s_addc_u32 s15, s7, 0
	s_bfe_i64 s[2:3], s[2:3], 0x100000
	v_writelane_b32 v253, s7, 36
	v_writelane_b32 v253, s14, 37
	s_ashr_i32 s17, s16, 31
	s_lshl_b64 s[6:7], s[16:17], 19
	v_writelane_b32 v253, s15, 38
	s_lshl_b64 s[14:15], s[2:3], 19
	v_writelane_b32 v253, s14, 39
	s_add_u32 s6, s18, s6
	s_load_dwordx16 s[36:51], s[0:1], 0x18
	v_writelane_b32 v253, s15, 40
	v_writelane_b32 v253, s18, 41
	s_addc_u32 s7, s19, s7
	s_add_u32 s14, s6, 0x40000
	v_writelane_b32 v253, s19, 42
	v_writelane_b32 v253, s6, 43
	s_addc_u32 s15, s7, 0
	s_lshl_b64 s[2:3], s[2:3], 20
	v_writelane_b32 v253, s7, 44
	v_writelane_b32 v253, s14, 45
	s_mov_b64 s[30:31], 0x80
	s_nop 0
	v_writelane_b32 v253, s15, 46
	v_writelane_b32 v253, s2, 47
	s_nop 1
	v_writelane_b32 v253, s3, 48
	s_mov_b32 s2, s16
	v_writelane_b32 v253, s2, 49
	s_nop 1
	v_writelane_b32 v253, s3, 50
	s_lshl_b64 s[2:3], s[16:17], 20
	s_add_u32 s6, s20, s2
	v_writelane_b32 v253, s20, 51
	s_addc_u32 s7, s21, s3
	s_load_dword s3, s[0:1], 0xd0
	v_writelane_b32 v253, s21, 52
	v_writelane_b32 v253, s22, 53
	s_mul_i32 s2, s27, s26
	s_waitcnt lgkmcnt(0)
	s_mul_i32 s2, s2, s3
	v_writelane_b32 v253, s23, 54
	v_writelane_b32 v253, s2, 55
	s_add_u32 s2, s6, 0x80000
	v_writelane_b32 v253, s6, 56
	s_addc_u32 s3, s7, 0
	v_cndmask_b32_e64 v201, 0, 1, s[22:23]
	v_writelane_b32 v253, s7, 57
	v_writelane_b32 v253, s2, 58
	s_movk_i32 s23, 0x7fff
	s_mov_b32 s22, 0xffff0000
	v_writelane_b32 v253, s3, 59
	s_abs_i32 s2, s12
	v_cvt_f32_u32_e32 v0, s2
	s_sub_i32 s3, 0, s2
	s_mov_b32 s12, s77
	v_rcp_iflag_f32_e32 v0, v0
	s_nop 0
	v_mul_f32_e32 v0, 0x4f7ffffe, v0
	v_cvt_u32_f32_e32 v0, v0
	s_nop 0
	v_readfirstlane_b32 s4, v0
	s_mul_i32 s3, s3, s4
	s_mul_hi_u32 s3, s4, s3
	s_add_i32 s4, s4, s3
	s_abs_i32 s3, s8
	s_mul_hi_u32 s4, s3, s4
	s_mul_i32 s4, s4, s2
	s_sub_i32 s3, s3, s4
	s_ashr_i32 s4, s8, 31
	s_sub_i32 s5, s3, s2
	s_cmp_ge_u32 s3, s2
	s_cselect_b32 s3, s5, s3
	s_sub_i32 s5, s3, s2
	s_cmp_ge_u32 s3, s2
	s_cselect_b32 s2, s5, s3
	s_xor_b32 s2, s2, s4
	s_sub_i32 s2, s2, s4
	s_add_i32 s2, s11, s2
	v_writelane_b32 v253, s2, 60
	s_add_u32 s2, s42, 16
	s_addc_u32 s3, s43, 0
	v_writelane_b32 v253, s2, 61
	s_load_dwordx4 s[4:7], s[0:1], 0xb0
	v_lshl_add_u32 v0, v200, 4, 0
	v_writelane_b32 v253, s3, 62
	s_add_u32 s2, s44, 16
	v_writelane_b32 v253, s36, 63
	s_addc_u32 s3, s45, 0
	v_add_u32_e32 v216, 0x20440, v0
	v_writelane_b32 v254, s37, 0
	v_writelane_b32 v254, s38, 1
	v_writelane_b32 v254, s39, 2
	v_writelane_b32 v254, s40, 3
	v_writelane_b32 v254, s41, 4
	v_writelane_b32 v254, s42, 5
	v_writelane_b32 v254, s43, 6
	v_writelane_b32 v254, s44, 7
	v_writelane_b32 v254, s45, 8
	v_writelane_b32 v254, s46, 9
	v_writelane_b32 v254, s47, 10
	v_writelane_b32 v254, s48, 11
	v_writelane_b32 v254, s49, 12
	v_writelane_b32 v254, s50, 13
	v_writelane_b32 v254, s51, 14
	v_writelane_b32 v254, s2, 15
	s_nop 1
	v_writelane_b32 v254, s3, 16
	v_writelane_b32 v254, s13, 17
	s_lshl_b32 s3, s13, 2
	v_writelane_b32 v254, s3, 18
	v_writelane_b32 v254, s28, 19
	s_lshl_b32 s3, s28, 2
	v_writelane_b32 v254, s3, 20
	s_add_u32 s3, s24, 0x23e40040
	v_writelane_b32 v254, s3, 21
	s_addc_u32 s3, s25, 0
	v_writelane_b32 v254, s3, 22
	s_add_i32 s3, 0, 0x8800
	v_writelane_b32 v254, s3, 23
	s_add_i32 s3, 0, 0x12a00
	v_writelane_b32 v254, s3, 24
	s_add_i32 s3, 0, 0x13a00
	v_writelane_b32 v254, s3, 25
	s_add_i32 s3, 0, 0x20000
	v_writelane_b32 v254, s3, 26
	s_add_i32 s3, 0, 0x20004
	v_writelane_b32 v254, s3, 27
	s_add_i32 s3, 0, 0x10200
	s_movk_i32 s2, 0x100
	v_writelane_b32 v254, s3, 28
	s_add_i32 s3, 0, 0x18400
	v_writelane_b32 v254, s3, 29
	v_cmp_gt_u32_e64 s[2:3], s2, v200
	s_nop 1
	v_writelane_b32 v254, s2, 30
	s_nop 1
	v_writelane_b32 v254, s3, 31
	s_mov_b64 s[2:3], -1
	v_writelane_b32 v254, s2, 32
	s_nop 1
	v_writelane_b32 v254, s3, 33
	s_mov_b32 s3, 0xbfe62e42
	v_writelane_b32 v254, s2, 34
	s_nop 1
	v_writelane_b32 v254, s3, 35
	s_mov_b32 s3, 0x3fc55555
	v_writelane_b32 v254, s2, 36
	s_nop 1
	v_writelane_b32 v254, s3, 37
	s_mov_b32 s3, 0x3fb99999
	v_writelane_b32 v254, s2, 38
	s_nop 1
	v_writelane_b32 v254, s3, 39
	s_mov_b32 s3, 0x3fb55555
	v_writelane_b32 v254, s2, 40
	s_nop 1
	v_writelane_b32 v254, s3, 41
	s_mov_b32 s3, 0x3fb24924
	v_writelane_b32 v254, s2, 42
	s_nop 1
	v_writelane_b32 v254, s3, 43
	s_mov_b32 s3, 0xc01921fb
	v_writelane_b32 v254, s2, 44
	s_nop 1
	v_writelane_b32 v254, s3, 45
	s_mov_b32 s3, 0x3fa99999
	v_writelane_b32 v254, s2, 46
	s_nop 1
	v_writelane_b32 v254, s3, 47
	s_mov_b32 s3, 0x3fa11111
	v_writelane_b32 v254, s2, 48
	s_nop 1
	v_writelane_b32 v254, s3, 49
	s_mov_b32 s3, 0x3f924924
	v_writelane_b32 v254, s2, 50
	s_nop 1
	v_writelane_b32 v254, s3, 51
	s_mov_b32 s3, 0x3f8c71c7
	v_writelane_b32 v254, s2, 52
	s_nop 1
	v_writelane_b32 v254, s3, 53
	s_mov_b32 s3, 0x3f711111
	v_writelane_b32 v254, s2, 54
	s_nop 1
	v_writelane_b32 v254, s3, 55
	s_mov_b32 s3, 0x3f638138
	v_writelane_b32 v254, s2, 56
	s_nop 1
	v_writelane_b32 v254, s3, 57
	s_mov_b32 s3, 0x3f4f07c1
	v_writelane_b32 v254, s2, 58
	s_nop 1
	v_writelane_b32 v254, s3, 59
	s_mov_b32 s3, 0x3fae1e1e
	v_writelane_b32 v254, s2, 60
	s_nop 1
	v_writelane_b32 v254, s3, 61
	s_mov_b32 s3, 0x3fac71c7
	v_writelane_b32 v254, s2, 62
	s_nop 1
	v_writelane_b32 v254, s3, 63
	s_mov_b32 s3, 0x3fa86186
	v_writelane_b32 v250, s2, 0
	s_nop 1
	v_writelane_b32 v250, s3, 1
	s_waitcnt lgkmcnt(0)
	v_writelane_b32 v250, s4, 2
	s_nop 1
	v_writelane_b32 v250, s5, 3
	v_writelane_b32 v250, s6, 4
	v_writelane_b32 v250, s7, 5
	s_load_dwordx4 s[4:7], s[0:1], 0x80
	s_waitcnt lgkmcnt(0)
	v_writelane_b32 v250, s4, 6
	s_nop 1
	v_writelane_b32 v250, s5, 7
	v_writelane_b32 v250, s6, 8
	v_writelane_b32 v250, s7, 9
	s_load_dwordx8 s[4:11], s[0:1], 0x60
	s_waitcnt lgkmcnt(0)
	v_writelane_b32 v250, s4, 10
	s_nop 1
	v_writelane_b32 v250, s5, 11
	v_writelane_b32 v250, s6, 12
	v_writelane_b32 v250, s7, 13
	v_writelane_b32 v250, s8, 14
	v_writelane_b32 v250, s9, 15
	v_writelane_b32 v250, s10, 16
	v_writelane_b32 v250, s11, 17
	v_writelane_b32 v250, s34, 18
	s_nop 1
	v_writelane_b32 v250, s35, 19
	v_writelane_b32 v250, s55, 20
	s_branch .LBB0_71

.LBB0_114:
	s_add_i32 s74, s74, 1
	v_readlane_b32 s17, v251, 38
	s_mul_i32 s17, s74, s17
	s_mul_hi_u32 s19, s74, s26
	s_add_i32 s19, s19, s17
	s_mul_i32 s17, s74, s26
	s_add_u32 s20, s17, s54
	s_addc_u32 s21, s19, s55
	v_cmp_gt_i64_e32 vcc, s[20:21], v[204:205]
	v_cmp_lt_i64_e64 s[40:41], s[20:21], v[202:203]
	s_cbranch_vccnz .LBB0_116
	s_ashr_i32 s16, s20, 31
	s_lshr_b32 s16, s16, 29
	s_add_i32 s16, s20, s16
	s_ashr_i32 s17, s16, 3
	s_and_b32 s16, s16, -8
	s_sub_i32 s16, s20, s16
	s_cmp_lt_i32 s16, 0
	s_movk_i32 s18, 0xd5
	s_cselect_b32 s18, s18, 0xd4
	s_mul_i32 s16, s16, s18
	s_add_i32 s16, s16, s17
	s_mul_hi_i32 s17, s16, 0x4d4873ed
	s_lshr_b32 s18, s17, 31
	s_ashr_i32 s17, s17, 6
	s_add_i32 s17, s17, s18
	s_lshl_b32 s18, s17, 2
	s_sub_i32 s19, 32, s18
	s_min_i32 s19, s19, 4
	s_abs_i32 s20, s19
	v_cvt_f32_u32_e32 v0, s20
	s_sub_i32 s28, 0, s20
	s_mul_i32 s21, s17, 0xd4
	s_sub_i32 s16, s16, s21
	v_rcp_iflag_f32_e32 v0, v0
	s_abs_i32 s21, s16
	s_xor_b32 s27, s16, s19
	s_ashr_i32 s27, s27, 31
	v_mul_f32_e32 v0, 0x4f7ffffe, v0
	v_cvt_u32_f32_e32 v0, v0
	s_mul_i32 s17, s17, 7
	v_readfirstlane_b32 s29, v0
	s_mul_i32 s28, s28, s29
	s_mul_hi_u32 s28, s29, s28
	s_add_i32 s29, s29, s28
	s_mul_hi_u32 s28, s21, s29
	s_mul_i32 s29, s28, s20
	s_sub_i32 s21, s21, s29
	s_add_i32 s33, s28, 1
	s_sub_i32 s29, s21, s20
	s_cmp_ge_u32 s21, s20
	s_cselect_b32 s28, s33, s28
	s_cselect_b32 s21, s29, s21
	s_add_i32 s29, s28, 1
	s_cmp_ge_u32 s21, s20
	s_cselect_b32 s20, s29, s28
	s_xor_b32 s20, s20, s27
	s_sub_i32 s20, s20, s27
	s_mul_i32 s19, s20, s19
	s_sub_i32 s16, s16, s19
	s_add_i32 s17, s17, s20
	s_add_i32 s16, s18, s16
	s_mul_hi_i32 s18, s17, 0x4d4873ed
	s_lshr_b32 s19, s18, 31
	s_ashr_i32 s18, s18, 4
	s_add_i32 s18, s18, s19
	s_mul_i32 s18, s18, 53
	s_sub_i32 s18, s17, s18
	v_readlane_b32 s17, v251, 0
	s_nop 3
	s_and_b32 s19, s17, 7
	s_lshr_b32 s17, s17, 5
	s_cmp_lt_u32 s17, 5
	s_cbranch_scc1 .Lmp1_A
	s_sub_i32 s20, 9, s17
	s_cmp_lt_u32 s74, s20
	s_cbranch_scc1 .Lmp1_H
	s_sub_i32 s21, s74, s20
	s_sub_i32 s20, s17, 5
	s_lshl_b32 s18, s20, 1
	s_lshr_b32 s20, s20, 1
	s_add_i32 s18, s18, s20
	s_add_i32 s18, s18, s21
	s_add_i32 s18, s18, 35
	s_branch .Lmp1_L
.Lmp1_H:
	s_add_i32 s20, s74, s19
	s_cmp_eq_u32 s17, 5
	s_cbranch_scc0 .Lmp1_H6
	s_and_b32 s18, s20, 1
	s_and_b32 s20, s20, 2
	s_lshl_b32 s20, s20, 2
	s_add_i32 s18, s18, s20
	s_add_i32 s18, s18, 12
	s_branch .Lmp1_D
.Lmp1_H6:
	s_cmp_eq_u32 s17, 6
	s_cbranch_scc0 .Lmp1_H7
	s_mul_i32 s21, s20, 11
	s_lshr_b32 s21, s21, 5
	s_mul_i32 s21, s21, 3
	s_sub_i32 s20, s20, s21
	s_min_u32 s18, s20, 1
	s_lshl_b32 s18, s18, 3
	s_lshr_b32 s20, s20, 1
	s_lshl_b32 s20, s20, 1
	s_add_i32 s18, s18, s20
	s_add_i32 s18, s18, 14
	s_branch .Lmp1_D
.Lmp1_H7:
	s_and_b32 s18, s20, 1
	s_lshl_b32 s18, s18, 3
	s_add_i32 s18, s18, 15
	s_branch .Lmp1_D
.Lmp1_A:
	s_mul_i32 s18, s74, 5
	s_add_i32 s18, s18, s17
.Lmp1_L:
	s_mul_i32 s20, s19, 5
	s_add_i32 s18, s18, s20
	s_cmp_ge_u32 s18, 44
	s_cbranch_scc0 .Lmp1_L2
	s_sub_i32 s18, s18, 44
.Lmp1_L2:
	s_cmp_lt_u32 s18, 12
	s_cbranch_scc1 .Lmp1_D
	s_cmp_lt_u32 s18, 16
	s_cselect_b32 s20, 4, 9
	s_add_i32 s18, s18, s20
.Lmp1_D:
.LBB0_116:
	s_ashr_i32 s17, s16, 31
	s_lshl_b64 s[20:21], s[16:17], 20
	v_readlane_b32 s28, v251, 10
	v_readlane_b32 s29, v251, 11
	s_add_u32 s20, s28, s20
	s_addc_u32 s21, s29, s21
	s_and_b64 s[28:29], s[40:41], exec
	s_cselect_b32 s17, s21, s1
	s_cselect_b32 s43, s20, s0
	s_ashr_i32 s19, s18, 31
	s_lshl_b64 s[28:29], s[18:19], 20
	s_add_u32 s36, s65, s28
	s_addc_u32 s37, s66, s29
	s_and_b64 s[28:29], s[40:41], exec
	s_cselect_b32 s19, s37, s3
	s_cselect_b32 s44, s36, s2
	s_add_u32 s0, s0, 0x80080
	s_addc_u32 s1, s1, 0
	s_add_u32 s45, s2, 0x100
	s_waitcnt lgkmcnt(0)
	v_mov_b32_e32 v2, 0
	s_addc_u32 s46, s3, 0
	s_mov_b32 s47, -2
	v_mov_b32_e32 v3, v2
	v_mov_b32_e32 v4, v2
	v_mov_b32_e32 v5, v2
	v_mov_b32_e32 v6, v2
	v_mov_b32_e32 v7, v2
	v_mov_b32_e32 v8, v2
	v_mov_b32_e32 v9, v2
	v_mov_b32_e32 v18, v2
	v_mov_b32_e32 v19, v2
	v_mov_b32_e32 v20, v2
	v_mov_b32_e32 v21, v2
	v_mov_b32_e32 v22, v2
	v_mov_b32_e32 v23, v2
	v_mov_b32_e32 v24, v2
	v_mov_b32_e32 v25, v2
	v_mov_b32_e32 v34, v2
	v_mov_b32_e32 v35, v2
	v_mov_b32_e32 v36, v2
	v_mov_b32_e32 v37, v2
	v_mov_b32_e32 v38, v2
	v_mov_b32_e32 v39, v2
	v_mov_b32_e32 v40, v2
	v_mov_b32_e32 v41, v2
	v_mov_b32_e32 v50, v2
	v_mov_b32_e32 v51, v2
	v_mov_b32_e32 v52, v2
	v_mov_b32_e32 v53, v2
	v_mov_b32_e32 v54, v2
	v_mov_b32_e32 v55, v2
	v_mov_b32_e32 v56, v2
	v_mov_b32_e32 v57, v2
	v_mov_b32_e32 v10, v2
	v_mov_b32_e32 v11, v2
	v_mov_b32_e32 v12, v2
	v_mov_b32_e32 v13, v2
	v_mov_b32_e32 v14, v2
	v_mov_b32_e32 v15, v2
	v_mov_b32_e32 v16, v2
	v_mov_b32_e32 v17, v2
	v_mov_b32_e32 v26, v2
	v_mov_b32_e32 v27, v2
	v_mov_b32_e32 v28, v2
	v_mov_b32_e32 v29, v2
	v_mov_b32_e32 v30, v2
	v_mov_b32_e32 v31, v2
	v_mov_b32_e32 v32, v2
	v_mov_b32_e32 v33, v2
	v_mov_b32_e32 v42, v2
	v_mov_b32_e32 v43, v2
	v_mov_b32_e32 v44, v2
	v_mov_b32_e32 v45, v2
	v_mov_b32_e32 v46, v2
	v_mov_b32_e32 v47, v2
	v_mov_b32_e32 v48, v2
	v_mov_b32_e32 v49, v2
	v_mov_b32_e32 v58, v2
	v_mov_b32_e32 v59, v2
	v_mov_b32_e32 v60, v2
	v_mov_b32_e32 v61, v2
	v_mov_b32_e32 v62, v2
	v_mov_b32_e32 v63, v2
	v_mov_b32_e32 v64, v2
	v_mov_b32_e32 v65, v2
	v_mov_b32_e32 v66, v2
	v_mov_b32_e32 v67, v2
	v_mov_b32_e32 v68, v2
	v_mov_b32_e32 v69, v2
	v_mov_b32_e32 v70, v2
	v_mov_b32_e32 v71, v2
	v_mov_b32_e32 v72, v2
	v_mov_b32_e32 v73, v2
	v_mov_b32_e32 v82, v2
	v_mov_b32_e32 v83, v2
	v_mov_b32_e32 v84, v2
	v_mov_b32_e32 v85, v2
	v_mov_b32_e32 v86, v2
	v_mov_b32_e32 v87, v2
	v_mov_b32_e32 v88, v2
	v_mov_b32_e32 v89, v2
	v_mov_b32_e32 v98, v2
	v_mov_b32_e32 v99, v2
	v_mov_b32_e32 v100, v2
	v_mov_b32_e32 v101, v2
	v_mov_b32_e32 v102, v2
	v_mov_b32_e32 v103, v2
	v_mov_b32_e32 v104, v2
	v_mov_b32_e32 v105, v2
	v_mov_b32_e32 v114, v2
	v_mov_b32_e32 v115, v2
	v_mov_b32_e32 v116, v2
	v_mov_b32_e32 v117, v2
	v_mov_b32_e32 v118, v2
	v_mov_b32_e32 v119, v2
	v_mov_b32_e32 v120, v2
	v_mov_b32_e32 v121, v2
	v_mov_b32_e32 v74, v2
	v_mov_b32_e32 v75, v2
	v_mov_b32_e32 v76, v2
	v_mov_b32_e32 v77, v2
	v_mov_b32_e32 v78, v2
	v_mov_b32_e32 v79, v2
	v_mov_b32_e32 v80, v2
	v_mov_b32_e32 v81, v2
	v_mov_b32_e32 v90, v2
	v_mov_b32_e32 v91, v2
	v_mov_b32_e32 v92, v2
	v_mov_b32_e32 v93, v2
	v_mov_b32_e32 v94, v2
	v_mov_b32_e32 v95, v2
	v_mov_b32_e32 v96, v2
	v_mov_b32_e32 v97, v2
	v_mov_b32_e32 v106, v2
	v_mov_b32_e32 v107, v2
	v_mov_b32_e32 v108, v2
	v_mov_b32_e32 v109, v2
	v_mov_b32_e32 v110, v2
	v_mov_b32_e32 v111, v2
	v_mov_b32_e32 v112, v2
	v_mov_b32_e32 v113, v2
	v_mov_b32_e32 v122, v2
	v_mov_b32_e32 v123, v2
	v_mov_b32_e32 v124, v2
	v_mov_b32_e32 v125, v2
	v_mov_b32_e32 v126, v2
	v_mov_b32_e32 v127, v2
	v_mov_b32_e32 v128, v2
	v_mov_b32_e32 v129, v2
